# P fragments without permlane32_swap: V tile kept in natural key order in LDS
# speedup vs baseline: 1.0025x; 1.0014x over previous
; #define LAS __attribute__((address_space(3)))
; __device__ __forceinline__ int v_st(int k, int c) { const int kk = (k & ~0xC) | ((k & 4) << 1) | ((k & 8) >> 1); return ((kk >> 3) * 4 + (c >> 5)) * 512 + ((kk & 7) * 32 + (c & 31)) * 2; }
; __device__ __forceinline__ int v_rd_base(int lane) { return ((lane & 3) << 3) | (((lane >> 2) & 3) << 6) | (((lane >> 4) & 1) << 5) | (((lane >> 5) & 1) << 8); }
; __device__ __forceinline__ void attn_block(const Ptrs& P, int b, int h, int qb, LAS char* lds) {
;     const int tid = threadIdx.x, wid = __builtin_amdgcn_readfirstlane(tid >> 6), lane = tid & 63, r32 = lane & 31, hi = lane >> 5;
;     const int grp = wid >> 2;
;     const int i0 = qb * QB, P0 = NMETA + i0;
;     const int NT = (P0 + QB - 1) / KVBLK + 1;
;     const bf16* Qw = P.q_() + ((size_t)(b * NH + h) * SEQ + i0 + wid * QBLK + r32) * DQK;
;     const __amdgpu_buffer_rsrc_t srdK = __builtin_amdgcn_make_buffer_rsrc((void*)(P.kn_() + (size_t)(b * NH + h) * LPAD * 128), (short)0, LPAD * 256, 0x00020000);
;     const __amdgpu_buffer_rsrc_t srdV = __builtin_amdgcn_make_buffer_rsrc((void*)(P.v_() + (size_t)(b * NH + h) * LPAD * 128), (short)0, LPAD * 256, 0x00020000);
;     const __amdgpu_buffer_rsrc_t srdR = __builtin_amdgcn_make_buffer_rsrc((void*)(P.kr_() + (size_t)b * LPAD * 64), (short)0, LPAD * 128, 0x00020000);
;     bf16x8 qr[12];
; #pragma unroll
;     for (int d0 = 0; d0 < 12; ++d0) qr[d0] = *(const bf16x8*)(Qw + d0 * 16 + hi * 8);
;     const int sr = tid >> 4, sc = (tid & 15) * 8, kws = OFF_K + KSWZ(sr, sc * 2), vst0 = OFF_V + v_st(sr, sc), vst1 = OFF_V + v_st(32 + sr, sc);
;     const int rr = tid >> 3, rc = tid & 7, rws = OFF_R + RSWZ(rr, rc);
;     const int qlo = P0 + wid * QBLK, qm = qlo + r32 - 4 * hi;
;     LAS float* wsf = (LAS float*)(lds + OFF_WS) + wid * 64; LAS float* li_l = wsf; LAS float* al_l = wsf + 32;
;     const int lbase = (int)(uintptr_t)(lds);
;     const int vb0 = lbase + OFF_V + v_rd_base(lane);
;     int kbase = lbase + OFF_K + KSWZ(r32, (hi * 8) * 2), rbase = lbase + OFF_R + RSWZ(r32, hi);
;     float m_reg = -1e30f, l_reg = 0.f; f32x16 o[4] = {};
;     bf16x8 st_k0, st_k1, st_v0, st_v1, st_r;
;     const unsigned gofk = (unsigned)((tid >> 4) * 128 + (tid & 15) * 8) * 2u, gofr = (unsigned)((tid >> 3) * 64 + (tid & 7) * 8) * 2u;
.LBB0_607:
	s_andn2_b64 vcc, exec, s[8:9]
	s_waitcnt vmcnt(0)
	s_barrier
	s_cbranch_vccnz .LBB0_634
	v_lshrrev_b32_e32 v3, 5, v1
	v_mov_b32_e32 v2, 0
	v_lshlrev_b32_e32 v4, 4, v3
	v_mov_b32_e32 v5, v2
	v_lshl_add_u64 v[4:5], s[86:87], 0, v[4:5]
	s_mov_b64 s[0:1], 0x9100000
	v_lshrrev_b32_e32 v9, 3, v0
	v_lshl_add_u64 v[168:169], v[4:5], 0, s[0:1]
	v_lshrrev_b32_e32 v4, 4, v0
	v_lshlrev_b32_e32 v5, 3, v0
	v_and_b32_e32 v9, 8, v9
	v_and_b32_e32 v6, 0x78, v5
	v_lshlrev_b32_e32 v7, 8, v4
	v_and_or_b32 v10, v4, 16, v9
	v_or_b32_e32 v4, 32, v4
	v_lshlrev_b32_e32 v6, 1, v6
	v_bfe_u32 v12, v0, 4, 2
	v_and_or_b32 v4, v4, 48, v9
	s_add_u32 s3, s86, 0xc100000
	v_lshrrev_b32_e32 v10, 1, v10
	v_bfe_u32 v11, v5, 5, 2
	v_and_or_b32 v12, v28, 4, v12
	v_and_b32_e32 v13, 48, v6
	v_lshrrev_b32_e32 v4, 1, v4
	s_addc_u32 s33, s87, 0
	v_or_b32_e32 v10, v10, v11
	v_lshl_or_b32 v12, v12, 6, v13
	v_or_b32_e32 v4, v4, v11
	s_add_u32 s35, s86, 0xe200000
	v_lshl_or_b32 v175, v10, 9, v12
	v_lshl_or_b32 v176, v4, 9, v12
	v_lshrrev_b32_e32 v175, 7, v0
	v_bfe_u32 v176, v0, 2, 2
	v_lshl_or_b32 v175, v175, 2, v176
	v_bfe_u32 v176, v0, 4, 3
	v_lshlrev_b32_e32 v176, 6, v176
	v_and_b32_e32 v250, 3, v0
	v_lshl_or_b32 v176, v250, 4, v176
	v_lshl_or_b32 v175, v175, 9, v176
	v_add_u32_e32 v176, 0x2000, v175
	v_lshlrev_b32_e32 v177, 4, v0
	s_movk_i32 s0, 0x70
	v_lshlrev_b32_e32 v12, 1, v0
	s_addc_u32 s58, s87, 0
	v_bitop3_b32 v4, v177, s0, v0 bitop3:0x48
	s_movk_i32 s0, 0x1f80
	v_and_b32_e32 v11, 0xc0, v177
	v_and_b32_e32 v12, 32, v12
	v_and_b32_e32 v5, 0x118, v5
	s_add_u32 s59, s86, 0x8f00000
	v_and_or_b32 v4, v177, s0, v4
	v_or3_b32 v5, v12, v11, v5
	v_bitop3_b32 v12, v3, v0, 15 bitop3:0x78
	v_lshrrev_b32_e32 v14, 1, v0
	s_addc_u32 s60, s87, 0
	v_lshlrev_b32_e32 v11, 8, v174
	v_bitop3_b32 v14, v3, v14, 7 bitop3:0x78
	v_add_u32_e32 v180, 0, v4
	v_lshlrev_b32_e32 v181, 2, v3
	s_add_i32 s1, 0, 0xc000
	v_lshlrev_b32_e32 v3, 4, v12
	v_and_b32_e32 v4, 30, v0
	v_and_b32_e32 v8, 0xf0, v0
	v_lshlrev_b32_e32 v13, 7, v174
	s_add_i32 s0, 0, 0x8000
	v_add_u32_e32 v182, s1, v5
	v_add3_u32 v183, v11, 0, v3
	v_lshlrev_b32_e32 v3, 4, v14
	v_lshlrev_b32_e32 v4, 1, v4
	v_mov_b32_e32 v5, v2
	v_bitop3_b32 v8, v6, v7, v8 bitop3:0xde
	v_or_b32_e32 v10, 0xc000, v175
	v_or_b32_e32 v9, 0xc000, v176
	v_add3_u32 v184, v13, s0, v3
	v_and_b32_e32 v3, 1, v0
	v_lshl_add_u64 v[4:5], s[86:87], 0, v[4:5]
	s_mov_b64 s[8:9], 0x4500000
	s_mov_b32 s11, 0x20000
	s_mov_b32 s7, 0
	s_mov_b32 s61, 0x8000
	v_or_b32_e32 v178, v6, v7
	v_add_u32_e32 v179, 0, v8
	v_cmp_gt_u32_e64 s[0:1], 32, v1
	v_cmp_eq_u32_e64 s[4:5], 0, v3
	v_lshl_add_u64 v[170:171], v[4:5], 0, s[8:9]
	v_or_b32_e32 v185, v181, v3
	v_sub_u32_e32 v186, v174, v181
	s_mov_b32 s10, 0x104000
	s_mov_b32 s18, 0x82000
	s_mov_b32 s19, s11
	s_movk_i32 s62, 0x180
	s_movk_i32 s63, 0x2000
	v_add_u32_e32 v187, 0, v175
	v_add_u32_e32 v188, 0, v176
	s_movk_i32 s64, 0x4000
	s_movk_i32 s65, 0x6000
	v_add_u32_e32 v189, 0, v10
	v_add_u32_e32 v190, 0, v9
	s_mov_b32 s66, 0xa000
	s_mov_b32 s67, 0x18000
	s_mov_b32 s68, 0x41000000
	s_mov_b32 s69, 0x10000
	s_mov_b32 s70, 0x12000
	s_mov_b32 s71, 0x1a000
	v_mov_b32_e32 v191, 0xff800000
	s_branch .LBB0_610

; __device__ __forceinline__ int crow(int r, int hi) { return (r & 3) + 8 * (r >> 2) + 4 * hi; }
; __device__ __forceinline__ void attn_block(const Ptrs& P, int b, int h, int qb, LAS char* lds) {
;     ...
;         if (!__all(pmax - m_reg <= THRL)) { const float mn = fmaxf(m_reg, pmax); alpha = __builtin_amdgcn_exp2f(m_reg - mn); m_reg = mn; }
; #pragma unroll
;         for (int r = 0; r < 16; ++r) { p0[r] = __builtin_amdgcn_exp2f(p0[r] - m_reg); p1[r] = __builtin_amdgcn_exp2f(p1[r] - m_reg); }
;         float ps = 0.f;
; #pragma unroll
;         for (int r = 0; r < 16; ++r) ps += p0[r];
; #pragma unroll
;         for (int r = 0; r < 16; ++r) ps += p1[r];
;         { auto sw_ = __builtin_amdgcn_permlane32_swap(__float_as_uint(ps), __float_as_uint(ps), false, false); ps = __uint_as_float(sw_[0]) + __uint_as_float(sw_[1]); }
;         l_reg = l_reg * alpha + ps;
;         PK4(p0, 0, pa0); PK4(p0, 8, pa1); PK4(p1, 0, pa2); PK4(p1, 8, pa3);
;         if (__any(alpha < 1.f)) { if (hi == 0) al_l[r32] = alpha; asm volatile("s_waitcnt lgkmcnt(0)" ::: "memory");
; #pragma unroll
;             for (int d_ = 0; d_ < 4; ++d_)
; #pragma unroll
;                 for (int r = 0; r < 16; ++r) o[d_][r] *= al_l[crow(r, hi)]; }
.Lattn_exp:
	v_exp_f32_e32 v84, v84
	v_exp_f32_e32 v85, v85
	v_exp_f32_e32 v86, v86
	v_exp_f32_e32 v87, v87
	v_exp_f32_e32 v88, v88
	v_exp_f32_e32 v89, v89
	v_exp_f32_e32 v90, v90
	v_exp_f32_e32 v91, v91
	v_exp_f32_e32 v92, v92
	v_exp_f32_e32 v93, v93
	v_exp_f32_e32 v94, v94
	v_exp_f32_e32 v95, v95
	v_exp_f32_e32 v96, v96
	v_exp_f32_e32 v97, v97
	v_exp_f32_e32 v98, v98
	v_exp_f32_e32 v99, v99
	v_exp_f32_e32 v68, v68
	v_add_f32_e32 v199, v84, v85
	v_exp_f32_e32 v69, v69
	v_add_f32_e32 v201, v86, v87
	v_exp_f32_e32 v70, v70
	v_add_f32_e32 v202, v88, v89
	v_exp_f32_e32 v71, v71
	v_add_f32_e32 v203, v90, v91
	v_exp_f32_e32 v72, v72
	v_add_f32_e32 v199, v92, v199
	v_exp_f32_e32 v73, v73
	v_add_f32_e32 v201, v93, v201
	v_exp_f32_e32 v74, v74
	v_add_f32_e32 v202, v94, v202
	v_exp_f32_e32 v75, v75
	v_add_f32_e32 v203, v95, v203
	v_exp_f32_e32 v76, v76
	v_add_f32_e32 v199, v96, v199
	v_exp_f32_e32 v77, v77
	v_add_f32_e32 v201, v97, v201
	v_exp_f32_e32 v78, v78
	v_add_f32_e32 v202, v98, v202
	v_exp_f32_e32 v79, v79
	v_add_f32_e32 v203, v99, v203
	v_exp_f32_e32 v80, v80
	v_exp_f32_e32 v81, v81
	v_exp_f32_e32 v82, v82
	v_exp_f32_e32 v83, v83
	v_add_f32_e32 v199, v68, v199
	v_add_f32_e32 v201, v69, v201
	v_add_f32_e32 v202, v70, v202
	v_add_f32_e32 v203, v71, v203
	v_add_f32_e32 v199, v72, v199
	v_add_f32_e32 v201, v73, v201
	v_add_f32_e32 v202, v74, v202
	v_add_f32_e32 v203, v75, v203
	v_add_f32_e32 v199, v76, v199
	v_add_f32_e32 v201, v77, v201
	v_add_f32_e32 v202, v78, v202
	v_add_f32_e32 v203, v79, v203
	v_add_f32_e32 v199, v80, v199
	v_add_f32_e32 v201, v81, v201
	v_add_f32_e32 v202, v82, v202
	v_add_f32_e32 v203, v83, v203
	v_add_f32_e32 v199, v199, v201
	v_add_f32_e32 v202, v202, v203
	v_cvt_pk_bf16_f32 v83, v82, v83
	v_cvt_pk_bf16_f32 v82, v80, v81
	v_cvt_pk_bf16_f32 v81, v78, v79
	v_cvt_pk_bf16_f32 v80, v76, v77
	v_cvt_pk_bf16_f32 v76, v68, v69
	v_cvt_pk_bf16_f32 v77, v70, v71
	v_cvt_pk_bf16_f32 v78, v72, v73
	v_cvt_pk_bf16_f32 v79, v74, v75
	v_cvt_pk_bf16_f32 v68, v84, v85
	v_cvt_pk_bf16_f32 v69, v86, v87
	v_cvt_pk_bf16_f32 v70, v88, v89
	v_cvt_pk_bf16_f32 v71, v90, v91
	v_add_f32_e32 v85, v199, v202
	v_mov_b32_e32 v84, v200
	v_mov_b32_e32 v86, v85
	v_cvt_pk_bf16_f32 v72, v92, v93
	v_cvt_pk_bf16_f32 v73, v94, v95
	v_cvt_pk_bf16_f32 v74, v96, v97
	v_cvt_pk_bf16_f32 v75, v98, v99
	v_permlane32_swap_b32_e32 v85, v86
	v_cmp_gt_f32_e32 vcc, 1.0, v84
	s_cbranch_vccz .LBB0_623
	s_and_saveexec_b64 s[22:23], s[0:1]
	ds_write_b32 v194, v84 offset:128
	s_or_b64 exec, exec, s[22:23]
	s_waitcnt lgkmcnt(0)
	ds_read_b128 v[88:91], v193 offset:224
	ds_read_b128 v[92:95], v193 offset:192
	ds_read_b128 v[96:99], v193 offset:160
	ds_read_b128 v[200:203], v193 offset:128
	s_waitcnt lgkmcnt(3)
	v_pk_mul_f32 v[66:67], v[66:67], v[90:91]
	s_waitcnt lgkmcnt(2)
	v_pk_mul_f32 v[62:63], v[62:63], v[94:95]
	s_waitcnt lgkmcnt(1)
	v_pk_mul_f32 v[58:59], v[58:59], v[98:99]
	s_waitcnt lgkmcnt(0)
	v_pk_mul_f32 v[54:55], v[54:55], v[202:203]
	v_pk_mul_f32 v[64:65], v[64:65], v[88:89]
	v_pk_mul_f32 v[60:61], v[60:61], v[92:93]
	v_pk_mul_f32 v[56:57], v[56:57], v[96:97]
	v_pk_mul_f32 v[52:53], v[52:53], v[200:201]
	v_pk_mul_f32 v[50:51], v[50:51], v[90:91]
	v_pk_mul_f32 v[46:47], v[46:47], v[94:95]
	v_pk_mul_f32 v[42:43], v[42:43], v[98:99]
	v_pk_mul_f32 v[38:39], v[38:39], v[202:203]
	v_pk_mul_f32 v[48:49], v[48:49], v[88:89]
	v_pk_mul_f32 v[44:45], v[44:45], v[92:93]
	v_pk_mul_f32 v[40:41], v[40:41], v[96:97]
	v_pk_mul_f32 v[36:37], v[36:37], v[200:201]
	v_pk_mul_f32 v[34:35], v[34:35], v[90:91]
	v_pk_mul_f32 v[30:31], v[30:31], v[94:95]
	v_pk_mul_f32 v[26:27], v[26:27], v[98:99]
	v_pk_mul_f32 v[22:23], v[22:23], v[202:203]
	v_pk_mul_f32 v[32:33], v[32:33], v[88:89]
	v_pk_mul_f32 v[28:29], v[28:29], v[92:93]
	v_pk_mul_f32 v[24:25], v[24:25], v[96:97]
	v_pk_mul_f32 v[20:21], v[20:21], v[200:201]
	v_pk_mul_f32 v[18:19], v[18:19], v[90:91]
	v_pk_mul_f32 v[14:15], v[14:15], v[94:95]
	v_pk_mul_f32 v[10:11], v[10:11], v[98:99]
	v_pk_mul_f32 v[6:7], v[6:7], v[202:203]
	v_pk_mul_f32 v[16:17], v[16:17], v[88:89]
	v_pk_mul_f32 v[12:13], v[12:13], v[92:93]
	v_pk_mul_f32 v[8:9], v[8:9], v[96:97]
	v_pk_mul_f32 v[4:5], v[4:5], v[200:201]

; __global__ void __launch_bounds__(NWAVES * 64, 2) hybrid_fwd(Args args) {
	.amdhsa_kernel _Z10hybrid_fwd4Args
		.amdhsa_group_segment_fixed_size 0
		.amdhsa_private_segment_fixed_size 0
		.amdhsa_kernarg_size 480
		.amdhsa_user_sgpr_count 2
		.amdhsa_user_sgpr_dispatch_ptr 0
		.amdhsa_user_sgpr_queue_ptr 0
		.amdhsa_user_sgpr_kernarg_segment_ptr 1
		.amdhsa_user_sgpr_dispatch_id 0
		.amdhsa_user_sgpr_kernarg_preload_length 0
		.amdhsa_user_sgpr_kernarg_preload_offset 0
		.amdhsa_user_sgpr_private_segment_size 0
		.amdhsa_uses_dynamic_stack 0
		.amdhsa_enable_private_segment 0
		.amdhsa_system_sgpr_workgroup_id_x 1
		.amdhsa_system_sgpr_workgroup_id_y 0
		.amdhsa_system_sgpr_workgroup_id_z 0
		.amdhsa_system_sgpr_workgroup_info 0
		.amdhsa_system_vgpr_workitem_id 0
		.amdhsa_next_free_vgpr 256
		.amdhsa_next_free_sgpr 98
		.amdhsa_accum_offset 256
		.amdhsa_reserve_vcc 1
		.amdhsa_float_round_mode_32 0
		.amdhsa_float_round_mode_16_64 0
		.amdhsa_float_denorm_mode_32 3
		.amdhsa_float_denorm_mode_16_64 3
		.amdhsa_dx10_clamp 1
		.amdhsa_ieee_mode 1
		.amdhsa_fp16_overflow 0
		.amdhsa_tg_split 0
		.amdhsa_exception_fp_ieee_invalid_op 0
		.amdhsa_exception_fp_denorm_src 0
		.amdhsa_exception_fp_ieee_div_zero 0
		.amdhsa_exception_fp_ieee_overflow 0
		.amdhsa_exception_fp_ieee_underflow 0
		.amdhsa_exception_fp_ieee_inexact 0
		.amdhsa_exception_int_div_zero 0
	.end_amdhsa_kernel

; __global__ void __launch_bounds__(NWAVES * 64, 2) hybrid_fwd(Args args) {
amdhsa.kernels:
  - .agpr_count:     0
    .args:
      - .offset:         0
        .size:           224
        .value_kind:     by_value
      - .offset:         224
        .size:           4
        .value_kind:     hidden_block_count_x
      - .offset:         228
        .size:           4
        .value_kind:     hidden_block_count_y
      - .offset:         232
        .size:           4
        .value_kind:     hidden_block_count_z
      - .offset:         236
        .size:           2
        .value_kind:     hidden_group_size_x
      - .offset:         238
        .size:           2
        .value_kind:     hidden_group_size_y
      - .offset:         240
        .size:           2
        .value_kind:     hidden_group_size_z
      - .offset:         242
        .size:           2
        .value_kind:     hidden_remainder_x
      - .offset:         244
        .size:           2
        .value_kind:     hidden_remainder_y
      - .offset:         246
        .size:           2
        .value_kind:     hidden_remainder_z
      - .offset:         264
        .size:           8
        .value_kind:     hidden_global_offset_x
      - .offset:         272
        .size:           8
        .value_kind:     hidden_global_offset_y
      - .offset:         280
        .size:           8
        .value_kind:     hidden_global_offset_z
      - .offset:         288
        .size:           2
        .value_kind:     hidden_grid_dims
      - .offset:         344
        .size:           4
        .value_kind:     hidden_dynamic_lds_size
    .group_segment_fixed_size: 0
    .kernarg_segment_align: 8
    .kernarg_segment_size: 480
    .language:       OpenCL C
    .language_version:
      - 2
      - 0
    .max_flat_workgroup_size: 512
    .name:           _Z10hybrid_fwd4Args
    .private_segment_fixed_size: 0
    .sgpr_count:     104
    .sgpr_spill_count: 54
    .symbol:         _Z10hybrid_fwd4Args.kd
    .uniform_work_group_size: 1
    .uses_dynamic_stack: false
    .vgpr_count:     256
    .vgpr_spill_count: 0
    .wavefront_size: 64
